# full-snake MFMA order: every consecutive MFMA pair shares its accumulator, srcA or srcB
# speedup vs baseline: 1.0092x; 1.0041x over previous
.LBB0_32:
	s_add_u32 s28, s54, 0xfff80080
	s_addc_u32 s29, s55, -1
	s_add_i32 s30, 0, 0x10000
	s_cmp_eq_u32 s27, 28
	s_cselect_b32 s79, s13, s29
	s_cselect_b32 s78, s16, s28
	s_cselect_b32 s69, s9, s26
	s_cselect_b32 s68, s24, s25
	s_add_i32 s31, 0, 0x14000
	v_add_u32_e32 v142, s30, v184
	v_add_u32_e32 v172, s31, v184
	ds_read_b128 v[130:133], v142
	ds_read_b128 v[134:137], v142 offset:1024
	ds_read_b128 v[138:141], v142 offset:2048
	ds_read_b128 v[142:145], v142 offset:3072
	ds_read_b128 v[146:149], v172
	ds_read_b128 v[150:153], v172 offset:1024
	ds_read_b128 v[154:157], v172 offset:2048
	ds_read_b128 v[172:175], v172 offset:3072
	v_lshl_add_u64 v[212:213], s[54:55], 0, v[166:167]
	s_add_i32 m0, s42, 0xc000
	ds_read_b128 v[176:179], v186
	ds_read_b128 v[180:183], v186 offset:1024
	ds_read_b128 v[188:191], v186 offset:2048
	ds_read_b128 v[192:195], v186 offset:3072
	ds_read_b128 v[196:199], v186 offset:4096
	ds_read_b128 v[200:203], v186 offset:5120
	ds_read_b128 v[204:207], v186 offset:6144
	ds_read_b128 v[208:211], v186 offset:7168
	global_load_lds_dwordx4 v[212:213], off
	v_lshl_add_u64 v[212:213], s[54:55], 0, v[168:169]
	s_add_i32 m0, s42, 0xe000
	s_nop 0
	global_load_lds_dwordx4 v[212:213], off
	s_waitcnt vmcnt(8)
	s_waitcnt lgkmcnt(0)
	s_barrier
	s_setprio 1
	s_waitcnt lgkmcnt(0)
	v_mfma_f32_16x16x32_bf16 v[126:129], v[130:133], v[176:179], v[126:129]
	v_mfma_f32_16x16x32_bf16 v[126:129], v[134:137], v[180:183], v[126:129]
	v_mfma_f32_16x16x32_bf16 v[110:113], v[134:137], v[192:195], v[110:113]
	v_mfma_f32_16x16x32_bf16 v[110:113], v[130:133], v[188:191], v[110:113]
	v_mfma_f32_16x16x32_bf16 v[94:97], v[130:133], v[196:199], v[94:97]
	v_mfma_f32_16x16x32_bf16 v[94:97], v[134:137], v[200:203], v[94:97]
	v_mfma_f32_16x16x32_bf16 v[78:81], v[134:137], v[208:211], v[78:81]
	v_mfma_f32_16x16x32_bf16 v[78:81], v[130:133], v[204:207], v[78:81]
	v_mfma_f32_16x16x32_bf16 v[74:77], v[138:141], v[204:207], v[74:77]
	v_mfma_f32_16x16x32_bf16 v[74:77], v[142:145], v[208:211], v[74:77]
	v_mfma_f32_16x16x32_bf16 v[90:93], v[142:145], v[200:203], v[90:93]
	v_mfma_f32_16x16x32_bf16 v[90:93], v[138:141], v[196:199], v[90:93]
	v_mfma_f32_16x16x32_bf16 v[106:109], v[138:141], v[188:191], v[106:109]
	v_mfma_f32_16x16x32_bf16 v[106:109], v[142:145], v[192:195], v[106:109]
	v_mfma_f32_16x16x32_bf16 v[122:125], v[142:145], v[180:183], v[122:125]
	v_mfma_f32_16x16x32_bf16 v[122:125], v[138:141], v[176:179], v[122:125]
	s_setprio 0
	s_setprio 1
	v_mfma_f32_16x16x32_bf16 v[118:121], v[146:149], v[176:179], v[118:121]
	v_mfma_f32_16x16x32_bf16 v[118:121], v[150:153], v[180:183], v[118:121]
	v_mfma_f32_16x16x32_bf16 v[102:105], v[150:153], v[192:195], v[102:105]
	v_mfma_f32_16x16x32_bf16 v[102:105], v[146:149], v[188:191], v[102:105]
	v_mfma_f32_16x16x32_bf16 v[86:89], v[146:149], v[196:199], v[86:89]
	v_mfma_f32_16x16x32_bf16 v[86:89], v[150:153], v[200:203], v[86:89]
	v_mfma_f32_16x16x32_bf16 v[70:73], v[150:153], v[208:211], v[70:73]
	v_mfma_f32_16x16x32_bf16 v[70:73], v[146:149], v[204:207], v[70:73]
	v_mfma_f32_16x16x32_bf16 v[66:69], v[154:157], v[204:207], v[66:69]
	v_mfma_f32_16x16x32_bf16 v[66:69], v[172:175], v[208:211], v[66:69]
	v_mfma_f32_16x16x32_bf16 v[82:85], v[172:175], v[200:203], v[82:85]
	v_mfma_f32_16x16x32_bf16 v[82:85], v[154:157], v[196:199], v[82:85]
	v_mfma_f32_16x16x32_bf16 v[98:101], v[154:157], v[188:191], v[98:101]
	v_mfma_f32_16x16x32_bf16 v[98:101], v[172:175], v[192:195], v[98:101]
	v_mfma_f32_16x16x32_bf16 v[114:117], v[172:175], v[180:183], v[114:117]
	v_mfma_f32_16x16x32_bf16 v[114:117], v[154:157], v[176:179], v[114:117]
	s_setprio 0
	s_barrier
	s_add_i32 s28, s30, s11
	v_lshl_add_u64 v[212:213], s[68:69], 0, v[160:161]
	s_mov_b32 m0, s28
	ds_read_b128 v[176:179], v186 offset:16384
	ds_read_b128 v[180:183], v186 offset:17408
	ds_read_b128 v[188:191], v186 offset:18432
	ds_read_b128 v[192:195], v186 offset:19456
	ds_read_b128 v[196:199], v186 offset:20480
	ds_read_b128 v[200:203], v186 offset:21504
	ds_read_b128 v[204:207], v186 offset:22528
	ds_read_b128 v[208:211], v186 offset:23552
	global_load_lds_dwordx4 v[212:213], off
	s_add_i32 m0, s28, 0x2000
	s_add_u32 s28, s68, 0x80000
	v_lshl_add_u64 v[232:233], s[68:69], 0, v[164:165]
	s_addc_u32 s29, s69, 0
	s_add_i32 s30, s31, s11
	global_load_lds_dwordx4 v[232:233], off
	v_lshl_add_u64 v[234:235], s[28:29], 0, v[160:161]
	s_mov_b32 m0, s30
	v_lshl_add_u64 v[236:237], s[78:79], 0, v[162:163]
	global_load_lds_dwordx4 v[234:235], off
	v_lshl_add_u64 v[234:235], s[28:29], 0, v[164:165]
	s_add_i32 m0, s30, 0x2000
	s_nop 0
	global_load_lds_dwordx4 v[234:235], off
	v_lshl_add_u64 v[234:235], s[78:79], 0, v[158:159]
	s_mov_b32 m0, s42
	s_nop 0
	global_load_lds_dwordx4 v[234:235], off
	s_mov_b32 m0, s57
	s_nop 0
	global_load_lds_dwordx4 v[236:237], off
	s_waitcnt vmcnt(8)
	s_waitcnt lgkmcnt(0)
	s_barrier
	s_setprio 1
	s_waitcnt lgkmcnt(0)
	v_mfma_f32_16x16x32_bf16 v[62:65], v[130:133], v[176:179], v[62:65]
	v_mfma_f32_16x16x32_bf16 v[62:65], v[134:137], v[180:183], v[62:65]
	v_mfma_f32_16x16x32_bf16 v[46:49], v[134:137], v[192:195], v[46:49]
	v_mfma_f32_16x16x32_bf16 v[46:49], v[130:133], v[188:191], v[46:49]
	v_mfma_f32_16x16x32_bf16 v[30:33], v[130:133], v[196:199], v[30:33]
	v_mfma_f32_16x16x32_bf16 v[30:33], v[134:137], v[200:203], v[30:33]
	v_mfma_f32_16x16x32_bf16 v[14:17], v[134:137], v[208:211], v[14:17]
	v_mfma_f32_16x16x32_bf16 v[14:17], v[130:133], v[204:207], v[14:17]
	v_mfma_f32_16x16x32_bf16 v[10:13], v[138:141], v[204:207], v[10:13]
	v_mfma_f32_16x16x32_bf16 v[10:13], v[142:145], v[208:211], v[10:13]
	v_mfma_f32_16x16x32_bf16 v[26:29], v[142:145], v[200:203], v[26:29]
	v_mfma_f32_16x16x32_bf16 v[26:29], v[138:141], v[196:199], v[26:29]
	v_mfma_f32_16x16x32_bf16 v[42:45], v[138:141], v[188:191], v[42:45]
	v_mfma_f32_16x16x32_bf16 v[42:45], v[142:145], v[192:195], v[42:45]
	v_mfma_f32_16x16x32_bf16 v[58:61], v[142:145], v[180:183], v[58:61]
	v_mfma_f32_16x16x32_bf16 v[58:61], v[138:141], v[176:179], v[58:61]
	s_setprio 0
	s_setprio 1
	v_mfma_f32_16x16x32_bf16 v[54:57], v[146:149], v[176:179], v[54:57]
	v_mfma_f32_16x16x32_bf16 v[54:57], v[150:153], v[180:183], v[54:57]
	v_mfma_f32_16x16x32_bf16 v[38:41], v[150:153], v[192:195], v[38:41]
	v_mfma_f32_16x16x32_bf16 v[38:41], v[146:149], v[188:191], v[38:41]
	v_mfma_f32_16x16x32_bf16 v[22:25], v[146:149], v[196:199], v[22:25]
	v_mfma_f32_16x16x32_bf16 v[22:25], v[150:153], v[200:203], v[22:25]
	v_mfma_f32_16x16x32_bf16 v[6:9], v[150:153], v[208:211], v[6:9]
	v_mfma_f32_16x16x32_bf16 v[6:9], v[146:149], v[204:207], v[6:9]
	v_mfma_f32_16x16x32_bf16 v[2:5], v[154:157], v[204:207], v[2:5]
	v_mfma_f32_16x16x32_bf16 v[2:5], v[172:175], v[208:211], v[2:5]
	v_mfma_f32_16x16x32_bf16 v[18:21], v[172:175], v[200:203], v[18:21]
	v_mfma_f32_16x16x32_bf16 v[18:21], v[154:157], v[196:199], v[18:21]
	v_mfma_f32_16x16x32_bf16 v[34:37], v[154:157], v[188:191], v[34:37]
	v_mfma_f32_16x16x32_bf16 v[34:37], v[172:175], v[192:195], v[34:37]
	v_mfma_f32_16x16x32_bf16 v[50:53], v[172:175], v[180:183], v[50:53]
	v_mfma_f32_16x16x32_bf16 v[50:53], v[154:157], v[176:179], v[50:53]
	s_setprio 0
	s_barrier
	s_add_i32 s30, 0, 0x18000
	s_add_i32 s31, 0, 0x1c000
	v_add_u32_e32 v142, s30, v184
	v_add_u32_e32 v172, s31, v184
	ds_read_b128 v[130:133], v142
	ds_read_b128 v[134:137], v142 offset:1024
	ds_read_b128 v[138:141], v142 offset:2048
	ds_read_b128 v[142:145], v142 offset:3072
	ds_read_b128 v[146:149], v172
	ds_read_b128 v[150:153], v172 offset:1024
	ds_read_b128 v[154:157], v172 offset:2048
	ds_read_b128 v[172:175], v172 offset:3072
	s_add_u32 s28, s78, 0x80000
	s_addc_u32 s29, s79, 0
	s_mov_b32 m0, s67
	v_lshl_add_u64 v[238:239], s[28:29], 0, v[158:159]
	ds_read_b128 v[176:179], v186 offset:32768
	ds_read_b128 v[180:183], v186 offset:33792
	ds_read_b128 v[188:191], v186 offset:34816
	ds_read_b128 v[192:195], v186 offset:35840
	ds_read_b128 v[196:199], v186 offset:36864
	ds_read_b128 v[200:203], v186 offset:37888
	ds_read_b128 v[204:207], v186 offset:38912
	ds_read_b128 v[208:211], v186 offset:39936
	global_load_lds_dwordx4 v[238:239], off
	v_lshl_add_u64 v[238:239], s[28:29], 0, v[162:163]
	s_mov_b32 m0, s72
	s_nop 0
	global_load_lds_dwordx4 v[238:239], off
	s_waitcnt vmcnt(8)
	s_waitcnt lgkmcnt(0)
	s_barrier
	s_setprio 1
	s_waitcnt lgkmcnt(0)
	v_mfma_f32_16x16x32_bf16 v[126:129], v[130:133], v[176:179], v[126:129]
	v_mfma_f32_16x16x32_bf16 v[126:129], v[134:137], v[180:183], v[126:129]
	v_mfma_f32_16x16x32_bf16 v[110:113], v[134:137], v[192:195], v[110:113]
	v_mfma_f32_16x16x32_bf16 v[110:113], v[130:133], v[188:191], v[110:113]
	v_mfma_f32_16x16x32_bf16 v[94:97], v[130:133], v[196:199], v[94:97]
	v_mfma_f32_16x16x32_bf16 v[94:97], v[134:137], v[200:203], v[94:97]
	v_mfma_f32_16x16x32_bf16 v[78:81], v[134:137], v[208:211], v[78:81]
	v_mfma_f32_16x16x32_bf16 v[78:81], v[130:133], v[204:207], v[78:81]
	v_mfma_f32_16x16x32_bf16 v[74:77], v[138:141], v[204:207], v[74:77]
	v_mfma_f32_16x16x32_bf16 v[74:77], v[142:145], v[208:211], v[74:77]
	v_mfma_f32_16x16x32_bf16 v[90:93], v[142:145], v[200:203], v[90:93]
	v_mfma_f32_16x16x32_bf16 v[90:93], v[138:141], v[196:199], v[90:93]
	v_mfma_f32_16x16x32_bf16 v[106:109], v[138:141], v[188:191], v[106:109]
	v_mfma_f32_16x16x32_bf16 v[106:109], v[142:145], v[192:195], v[106:109]
	v_mfma_f32_16x16x32_bf16 v[122:125], v[142:145], v[180:183], v[122:125]
	v_mfma_f32_16x16x32_bf16 v[122:125], v[138:141], v[176:179], v[122:125]
	s_setprio 0
	s_setprio 1
	v_mfma_f32_16x16x32_bf16 v[118:121], v[146:149], v[176:179], v[118:121]
	v_mfma_f32_16x16x32_bf16 v[118:121], v[150:153], v[180:183], v[118:121]
	v_mfma_f32_16x16x32_bf16 v[102:105], v[150:153], v[192:195], v[102:105]
	v_mfma_f32_16x16x32_bf16 v[102:105], v[146:149], v[188:191], v[102:105]
	v_mfma_f32_16x16x32_bf16 v[86:89], v[146:149], v[196:199], v[86:89]
	v_mfma_f32_16x16x32_bf16 v[86:89], v[150:153], v[200:203], v[86:89]
	v_mfma_f32_16x16x32_bf16 v[70:73], v[150:153], v[208:211], v[70:73]
	v_mfma_f32_16x16x32_bf16 v[70:73], v[146:149], v[204:207], v[70:73]
	v_mfma_f32_16x16x32_bf16 v[66:69], v[154:157], v[204:207], v[66:69]
	v_mfma_f32_16x16x32_bf16 v[66:69], v[172:175], v[208:211], v[66:69]
	v_mfma_f32_16x16x32_bf16 v[82:85], v[172:175], v[200:203], v[82:85]
	v_mfma_f32_16x16x32_bf16 v[82:85], v[154:157], v[196:199], v[82:85]
	v_mfma_f32_16x16x32_bf16 v[98:101], v[154:157], v[188:191], v[98:101]
	v_mfma_f32_16x16x32_bf16 v[98:101], v[172:175], v[192:195], v[98:101]
	v_mfma_f32_16x16x32_bf16 v[114:117], v[172:175], v[180:183], v[114:117]
	v_mfma_f32_16x16x32_bf16 v[114:117], v[154:157], v[176:179], v[114:117]
	s_setprio 0
	s_barrier
	s_add_i32 s28, s30, s11
	v_lshl_add_u64 v[212:213], v[212:213], 0, s[62:63]
	s_mov_b32 m0, s28
	ds_read_b128 v[176:179], v186 offset:49152
	ds_read_b128 v[180:183], v186 offset:50176
	ds_read_b128 v[188:191], v186 offset:51200
	ds_read_b128 v[192:195], v186 offset:52224
	ds_read_b128 v[196:199], v186 offset:53248
	ds_read_b128 v[200:203], v186 offset:54272
	ds_read_b128 v[204:207], v186 offset:55296
	ds_read_b128 v[208:211], v186 offset:56320
	global_load_lds_dwordx4 v[212:213], off
	s_add_i32 m0, s28, 0x2000
	s_add_u32 s28, s68, 0x80080
	v_lshl_add_u64 v[212:213], v[232:233], 0, s[62:63]
	s_addc_u32 s29, s69, 0
	s_add_i32 s30, s31, s11
	global_load_lds_dwordx4 v[212:213], off
	v_lshl_add_u64 v[212:213], s[28:29], 0, v[160:161]
	s_mov_b32 m0, s30
	s_nop 0
	global_load_lds_dwordx4 v[212:213], off
	v_lshl_add_u64 v[212:213], s[28:29], 0, v[164:165]
	s_add_i32 m0, s30, 0x2000
	s_nop 0
	global_load_lds_dwordx4 v[212:213], off
	v_lshl_add_u64 v[212:213], v[234:235], 0, s[62:63]
	s_mov_b32 m0, s18
	s_nop 0
	global_load_lds_dwordx4 v[212:213], off
	v_lshl_add_u64 v[212:213], v[236:237], 0, s[62:63]
	s_mov_b32 m0, s19
	s_nop 0
	global_load_lds_dwordx4 v[212:213], off
	s_waitcnt vmcnt(8)
	s_waitcnt lgkmcnt(0)
	s_barrier
	s_setprio 1
	s_waitcnt lgkmcnt(0)
	v_mfma_f32_16x16x32_bf16 v[62:65], v[130:133], v[176:179], v[62:65]
	v_mfma_f32_16x16x32_bf16 v[62:65], v[134:137], v[180:183], v[62:65]
	v_mfma_f32_16x16x32_bf16 v[46:49], v[134:137], v[192:195], v[46:49]
	v_mfma_f32_16x16x32_bf16 v[46:49], v[130:133], v[188:191], v[46:49]
	v_mfma_f32_16x16x32_bf16 v[30:33], v[130:133], v[196:199], v[30:33]
	v_mfma_f32_16x16x32_bf16 v[30:33], v[134:137], v[200:203], v[30:33]
	v_mfma_f32_16x16x32_bf16 v[14:17], v[134:137], v[208:211], v[14:17]
	v_mfma_f32_16x16x32_bf16 v[14:17], v[130:133], v[204:207], v[14:17]
	v_mfma_f32_16x16x32_bf16 v[10:13], v[138:141], v[204:207], v[10:13]
	v_mfma_f32_16x16x32_bf16 v[10:13], v[142:145], v[208:211], v[10:13]
	v_mfma_f32_16x16x32_bf16 v[26:29], v[142:145], v[200:203], v[26:29]
	v_mfma_f32_16x16x32_bf16 v[26:29], v[138:141], v[196:199], v[26:29]
	v_mfma_f32_16x16x32_bf16 v[42:45], v[138:141], v[188:191], v[42:45]
	v_mfma_f32_16x16x32_bf16 v[42:45], v[142:145], v[192:195], v[42:45]
	v_mfma_f32_16x16x32_bf16 v[58:61], v[142:145], v[180:183], v[58:61]
	v_mfma_f32_16x16x32_bf16 v[58:61], v[138:141], v[176:179], v[58:61]
	s_setprio 0
	s_setprio 1
	v_mfma_f32_16x16x32_bf16 v[54:57], v[146:149], v[176:179], v[54:57]
	v_mfma_f32_16x16x32_bf16 v[54:57], v[150:153], v[180:183], v[54:57]
	v_mfma_f32_16x16x32_bf16 v[38:41], v[150:153], v[192:195], v[38:41]
	v_mfma_f32_16x16x32_bf16 v[38:41], v[146:149], v[188:191], v[38:41]
	v_mfma_f32_16x16x32_bf16 v[22:25], v[146:149], v[196:199], v[22:25]
	v_mfma_f32_16x16x32_bf16 v[22:25], v[150:153], v[200:203], v[22:25]
	v_mfma_f32_16x16x32_bf16 v[6:9], v[150:153], v[208:211], v[6:9]
	v_mfma_f32_16x16x32_bf16 v[6:9], v[146:149], v[204:207], v[6:9]
	v_mfma_f32_16x16x32_bf16 v[2:5], v[154:157], v[204:207], v[2:5]
	v_mfma_f32_16x16x32_bf16 v[2:5], v[172:175], v[208:211], v[2:5]
	v_mfma_f32_16x16x32_bf16 v[18:21], v[172:175], v[200:203], v[18:21]
	v_mfma_f32_16x16x32_bf16 v[18:21], v[154:157], v[196:199], v[18:21]
	v_mfma_f32_16x16x32_bf16 v[34:37], v[154:157], v[188:191], v[34:37]
	v_mfma_f32_16x16x32_bf16 v[34:37], v[172:175], v[192:195], v[34:37]
	v_mfma_f32_16x16x32_bf16 v[50:53], v[172:175], v[180:183], v[50:53]
	v_mfma_f32_16x16x32_bf16 v[50:53], v[154:157], v[176:179], v[50:53]
	s_setprio 0
	s_barrier
	s_add_i32 s27, s27, 2
	s_add_u32 s54, s54, 0x100
	s_addc_u32 s55, s55, 0
	s_add_u32 s25, s25, 0x100
	s_addc_u32 s26, s26, 0
	s_cmp_gt_u32 s27, 29
	s_cbranch_scc0 .LBB0_32
	s_and_b64 vcc, exec, s[2:3]
	s_cbranch_vccz .LBB0_35
	s_barrier

.LBB0_132:
	s_add_u32 s23, s48, 0xfff80080
	s_addc_u32 s24, s49, -1
	s_add_i32 s25, 0, 0x10000
	s_cmp_eq_u32 s22, 28
	s_cselect_b32 s69, s3, s24
	s_cselect_b32 s68, s18, s23
	s_cselect_b32 s51, s1, s21
	s_cselect_b32 s50, s19, s20
	s_add_i32 s23, 0, 0x14000
	v_add_u32_e32 v156, s25, v165
	v_add_u32_e32 v169, s23, v165
	ds_read_b128 v[144:147], v156
	ds_read_b128 v[148:151], v156 offset:1024
	ds_read_b128 v[152:155], v156 offset:2048
	ds_read_b128 v[156:159], v156 offset:3072
	ds_read_b128 v[160:163], v169
	ds_read_b128 v[170:173], v169 offset:1024
	ds_read_b128 v[174:177], v169 offset:2048
	ds_read_b128 v[178:181], v169 offset:3072
	v_lshl_add_u64 v[232:233], s[48:49], 0, v[140:141]
	s_add_i32 m0, s45, 0xc000
	ds_read_b128 v[182:185], v168
	ds_read_b128 v[186:189], v168 offset:1024
	ds_read_b128 v[190:193], v168 offset:2048
	ds_read_b128 v[194:197], v168 offset:3072
	ds_read_b128 v[198:201], v168 offset:4096
	ds_read_b128 v[202:205], v168 offset:5120
	ds_read_b128 v[206:209], v168 offset:6144
	ds_read_b128 v[210:213], v168 offset:7168
	global_load_lds_dwordx4 v[232:233], off
	v_lshl_add_u64 v[232:233], s[48:49], 0, v[142:143]
	s_add_i32 m0, s45, 0xe000
	s_nop 0
	global_load_lds_dwordx4 v[232:233], off
	s_waitcnt vmcnt(8)
	s_waitcnt lgkmcnt(0)
	s_barrier
	s_setprio 1
	s_waitcnt lgkmcnt(0)
	v_mfma_f32_16x16x32_bf16 v[126:129], v[144:147], v[182:185], v[126:129]
	v_mfma_f32_16x16x32_bf16 v[126:129], v[148:151], v[186:189], v[126:129]
	v_mfma_f32_16x16x32_bf16 v[110:113], v[148:151], v[194:197], v[110:113]
	v_mfma_f32_16x16x32_bf16 v[110:113], v[144:147], v[190:193], v[110:113]
	v_mfma_f32_16x16x32_bf16 v[102:105], v[144:147], v[198:201], v[102:105]
	v_mfma_f32_16x16x32_bf16 v[102:105], v[148:151], v[202:205], v[102:105]
	v_mfma_f32_16x16x32_bf16 v[86:89], v[148:151], v[210:213], v[86:89]
	v_mfma_f32_16x16x32_bf16 v[86:89], v[144:147], v[206:209], v[86:89]
	v_mfma_f32_16x16x32_bf16 v[78:81], v[152:155], v[206:209], v[78:81]
	v_mfma_f32_16x16x32_bf16 v[78:81], v[156:159], v[210:213], v[78:81]
	v_mfma_f32_16x16x32_bf16 v[94:97], v[156:159], v[202:205], v[94:97]
	v_mfma_f32_16x16x32_bf16 v[94:97], v[152:155], v[198:201], v[94:97]
	v_mfma_f32_16x16x32_bf16 v[106:109], v[152:155], v[190:193], v[106:109]
	v_mfma_f32_16x16x32_bf16 v[106:109], v[156:159], v[194:197], v[106:109]
	v_mfma_f32_16x16x32_bf16 v[122:125], v[156:159], v[186:189], v[122:125]
	v_mfma_f32_16x16x32_bf16 v[122:125], v[152:155], v[182:185], v[122:125]
	s_setprio 0
	s_setprio 1
	v_mfma_f32_16x16x32_bf16 v[118:121], v[160:163], v[182:185], v[118:121]
	v_mfma_f32_16x16x32_bf16 v[118:121], v[170:173], v[186:189], v[118:121]
	v_mfma_f32_16x16x32_bf16 v[98:101], v[170:173], v[194:197], v[98:101]
	v_mfma_f32_16x16x32_bf16 v[98:101], v[160:163], v[190:193], v[98:101]
	v_mfma_f32_16x16x32_bf16 v[82:85], v[160:163], v[198:201], v[82:85]
	v_mfma_f32_16x16x32_bf16 v[82:85], v[170:173], v[202:205], v[82:85]
	v_mfma_f32_16x16x32_bf16 v[70:73], v[170:173], v[210:213], v[70:73]
	v_mfma_f32_16x16x32_bf16 v[70:73], v[160:163], v[206:209], v[70:73]
	v_mfma_f32_16x16x32_bf16 v[66:69], v[174:177], v[206:209], v[66:69]
	v_mfma_f32_16x16x32_bf16 v[66:69], v[178:181], v[210:213], v[66:69]
	v_mfma_f32_16x16x32_bf16 v[74:77], v[178:181], v[202:205], v[74:77]
	v_mfma_f32_16x16x32_bf16 v[74:77], v[174:177], v[198:201], v[74:77]
	v_mfma_f32_16x16x32_bf16 v[90:93], v[174:177], v[190:193], v[90:93]
	v_mfma_f32_16x16x32_bf16 v[90:93], v[178:181], v[194:197], v[90:93]
	v_mfma_f32_16x16x32_bf16 v[114:117], v[178:181], v[186:189], v[114:117]
	v_mfma_f32_16x16x32_bf16 v[114:117], v[174:177], v[182:185], v[114:117]
	s_setprio 0
	s_barrier
	s_add_i32 s24, s25, s16
	v_lshl_add_u64 v[232:233], s[50:51], 0, v[132:133]
	s_mov_b32 m0, s24
	ds_read_b128 v[182:185], v168 offset:16384
	ds_read_b128 v[186:189], v168 offset:17408
	ds_read_b128 v[190:193], v168 offset:18432
	ds_read_b128 v[194:197], v168 offset:19456
	ds_read_b128 v[198:201], v168 offset:20480
	ds_read_b128 v[202:205], v168 offset:21504
	ds_read_b128 v[206:209], v168 offset:22528
	ds_read_b128 v[210:213], v168 offset:23552
	global_load_lds_dwordx4 v[232:233], off
	s_add_i32 m0, s24, 0x2000
	s_add_u32 s24, s50, 0x80000
	v_lshl_add_u64 v[234:235], s[50:51], 0, v[136:137]
	s_addc_u32 s25, s51, 0
	s_add_i32 s23, s23, s16
	global_load_lds_dwordx4 v[234:235], off
	v_lshl_add_u64 v[236:237], s[24:25], 0, v[132:133]
	s_mov_b32 m0, s23
	v_lshl_add_u64 v[238:239], s[68:69], 0, v[134:135]
	global_load_lds_dwordx4 v[236:237], off
	v_lshl_add_u64 v[236:237], s[24:25], 0, v[136:137]
	s_add_i32 m0, s23, 0x2000
	s_nop 0
	global_load_lds_dwordx4 v[236:237], off
	v_lshl_add_u64 v[236:237], s[68:69], 0, v[130:131]
	s_mov_b32 m0, s45
	s_nop 0
	global_load_lds_dwordx4 v[236:237], off
	s_mov_b32 m0, s57
	s_nop 0
	global_load_lds_dwordx4 v[238:239], off
	s_waitcnt vmcnt(8)
	s_waitcnt lgkmcnt(0)
	s_barrier
	s_setprio 1
	s_waitcnt lgkmcnt(0)
	v_mfma_f32_16x16x32_bf16 v[62:65], v[144:147], v[182:185], v[62:65]
	v_mfma_f32_16x16x32_bf16 v[62:65], v[148:151], v[186:189], v[62:65]
	v_mfma_f32_16x16x32_bf16 v[54:57], v[148:151], v[194:197], v[54:57]
	v_mfma_f32_16x16x32_bf16 v[54:57], v[144:147], v[190:193], v[54:57]
	v_mfma_f32_16x16x32_bf16 v[38:41], v[144:147], v[198:201], v[38:41]
	v_mfma_f32_16x16x32_bf16 v[38:41], v[148:151], v[202:205], v[38:41]
	v_mfma_f32_16x16x32_bf16 v[22:25], v[148:151], v[210:213], v[22:25]
	v_mfma_f32_16x16x32_bf16 v[22:25], v[144:147], v[206:209], v[22:25]
	v_mfma_f32_16x16x32_bf16 v[14:17], v[152:155], v[206:209], v[14:17]
	v_mfma_f32_16x16x32_bf16 v[14:17], v[156:159], v[210:213], v[14:17]
	v_mfma_f32_16x16x32_bf16 v[30:33], v[156:159], v[202:205], v[30:33]
	v_mfma_f32_16x16x32_bf16 v[30:33], v[152:155], v[198:201], v[30:33]
	v_mfma_f32_16x16x32_bf16 v[46:49], v[152:155], v[190:193], v[46:49]
	v_mfma_f32_16x16x32_bf16 v[46:49], v[156:159], v[194:197], v[46:49]
	v_mfma_f32_16x16x32_bf16 v[58:61], v[156:159], v[186:189], v[58:61]
	v_mfma_f32_16x16x32_bf16 v[58:61], v[152:155], v[182:185], v[58:61]
	s_setprio 0
	s_setprio 1
	v_mfma_f32_16x16x32_bf16 v[50:53], v[160:163], v[182:185], v[50:53]
	v_mfma_f32_16x16x32_bf16 v[50:53], v[170:173], v[186:189], v[50:53]
	v_mfma_f32_16x16x32_bf16 v[34:37], v[170:173], v[194:197], v[34:37]
	v_mfma_f32_16x16x32_bf16 v[34:37], v[160:163], v[190:193], v[34:37]
	v_mfma_f32_16x16x32_bf16 v[18:21], v[160:163], v[198:201], v[18:21]
	v_mfma_f32_16x16x32_bf16 v[18:21], v[170:173], v[202:205], v[18:21]
	v_mfma_f32_16x16x32_bf16 v[6:9], v[170:173], v[210:213], v[6:9]
	v_mfma_f32_16x16x32_bf16 v[6:9], v[160:163], v[206:209], v[6:9]
	v_mfma_f32_16x16x32_bf16 v[2:5], v[174:177], v[206:209], v[2:5]
	v_mfma_f32_16x16x32_bf16 v[2:5], v[178:181], v[210:213], v[2:5]
	v_mfma_f32_16x16x32_bf16 v[10:13], v[178:181], v[202:205], v[10:13]
	v_mfma_f32_16x16x32_bf16 v[10:13], v[174:177], v[198:201], v[10:13]
	v_mfma_f32_16x16x32_bf16 v[26:29], v[174:177], v[190:193], v[26:29]
	v_mfma_f32_16x16x32_bf16 v[26:29], v[178:181], v[194:197], v[26:29]
	v_mfma_f32_16x16x32_bf16 v[42:45], v[178:181], v[186:189], v[42:45]
	v_mfma_f32_16x16x32_bf16 v[42:45], v[174:177], v[182:185], v[42:45]
	s_setprio 0
	s_barrier
	s_add_i32 s23, 0, 0x18000
	s_add_i32 s26, 0, 0x1c000
	v_add_u32_e32 v156, s23, v165
	v_add_u32_e32 v169, s26, v165
	ds_read_b128 v[144:147], v156
	ds_read_b128 v[148:151], v156 offset:1024
	ds_read_b128 v[152:155], v156 offset:2048
	ds_read_b128 v[156:159], v156 offset:3072
	ds_read_b128 v[160:163], v169
	ds_read_b128 v[170:173], v169 offset:1024
	ds_read_b128 v[174:177], v169 offset:2048
	ds_read_b128 v[178:181], v169 offset:3072
	s_add_u32 s24, s68, 0x80000
	s_addc_u32 s25, s69, 0
	s_mov_b32 m0, s42
	v_lshl_add_u64 v[240:241], s[24:25], 0, v[130:131]
	ds_read_b128 v[182:185], v168 offset:32768
	ds_read_b128 v[186:189], v168 offset:33792
	ds_read_b128 v[190:193], v168 offset:34816
	ds_read_b128 v[194:197], v168 offset:35840
	ds_read_b128 v[198:201], v168 offset:36864
	ds_read_b128 v[202:205], v168 offset:37888
	ds_read_b128 v[206:209], v168 offset:38912
	ds_read_b128 v[210:213], v168 offset:39936
	global_load_lds_dwordx4 v[240:241], off
	v_lshl_add_u64 v[240:241], s[24:25], 0, v[134:135]
	s_mov_b32 m0, s6
	s_nop 0
	global_load_lds_dwordx4 v[240:241], off
	s_waitcnt vmcnt(8)
	s_waitcnt lgkmcnt(0)
	s_barrier
	s_setprio 1
	s_waitcnt lgkmcnt(0)
	v_mfma_f32_16x16x32_bf16 v[126:129], v[144:147], v[182:185], v[126:129]
	v_mfma_f32_16x16x32_bf16 v[126:129], v[148:151], v[186:189], v[126:129]
	v_mfma_f32_16x16x32_bf16 v[110:113], v[148:151], v[194:197], v[110:113]
	v_mfma_f32_16x16x32_bf16 v[110:113], v[144:147], v[190:193], v[110:113]
	v_mfma_f32_16x16x32_bf16 v[102:105], v[144:147], v[198:201], v[102:105]
	v_mfma_f32_16x16x32_bf16 v[102:105], v[148:151], v[202:205], v[102:105]
	v_mfma_f32_16x16x32_bf16 v[86:89], v[148:151], v[210:213], v[86:89]
	v_mfma_f32_16x16x32_bf16 v[86:89], v[144:147], v[206:209], v[86:89]
	v_mfma_f32_16x16x32_bf16 v[78:81], v[152:155], v[206:209], v[78:81]
	v_mfma_f32_16x16x32_bf16 v[78:81], v[156:159], v[210:213], v[78:81]
	v_mfma_f32_16x16x32_bf16 v[94:97], v[156:159], v[202:205], v[94:97]
	v_mfma_f32_16x16x32_bf16 v[94:97], v[152:155], v[198:201], v[94:97]
	v_mfma_f32_16x16x32_bf16 v[106:109], v[152:155], v[190:193], v[106:109]
	v_mfma_f32_16x16x32_bf16 v[106:109], v[156:159], v[194:197], v[106:109]
	v_mfma_f32_16x16x32_bf16 v[122:125], v[156:159], v[186:189], v[122:125]
	v_mfma_f32_16x16x32_bf16 v[122:125], v[152:155], v[182:185], v[122:125]
	s_setprio 0
	s_setprio 1
	v_mfma_f32_16x16x32_bf16 v[118:121], v[160:163], v[182:185], v[118:121]
	v_mfma_f32_16x16x32_bf16 v[118:121], v[170:173], v[186:189], v[118:121]
	v_mfma_f32_16x16x32_bf16 v[98:101], v[170:173], v[194:197], v[98:101]
	v_mfma_f32_16x16x32_bf16 v[98:101], v[160:163], v[190:193], v[98:101]
	v_mfma_f32_16x16x32_bf16 v[82:85], v[160:163], v[198:201], v[82:85]
	v_mfma_f32_16x16x32_bf16 v[82:85], v[170:173], v[202:205], v[82:85]
	v_mfma_f32_16x16x32_bf16 v[70:73], v[170:173], v[210:213], v[70:73]
	v_mfma_f32_16x16x32_bf16 v[70:73], v[160:163], v[206:209], v[70:73]
	v_mfma_f32_16x16x32_bf16 v[66:69], v[174:177], v[206:209], v[66:69]
	v_mfma_f32_16x16x32_bf16 v[66:69], v[178:181], v[210:213], v[66:69]
	v_mfma_f32_16x16x32_bf16 v[74:77], v[178:181], v[202:205], v[74:77]
	v_mfma_f32_16x16x32_bf16 v[74:77], v[174:177], v[198:201], v[74:77]
	v_mfma_f32_16x16x32_bf16 v[90:93], v[174:177], v[190:193], v[90:93]
	v_mfma_f32_16x16x32_bf16 v[90:93], v[178:181], v[194:197], v[90:93]
	v_mfma_f32_16x16x32_bf16 v[114:117], v[178:181], v[186:189], v[114:117]
	v_mfma_f32_16x16x32_bf16 v[114:117], v[174:177], v[182:185], v[114:117]
	s_setprio 0
	s_barrier
	s_add_i32 s23, s23, s16
	v_lshl_add_u64 v[232:233], v[232:233], 0, s[62:63]
	s_mov_b32 m0, s23
	ds_read_b128 v[182:185], v168 offset:49152
	ds_read_b128 v[186:189], v168 offset:50176
	ds_read_b128 v[190:193], v168 offset:51200
	ds_read_b128 v[194:197], v168 offset:52224
	ds_read_b128 v[198:201], v168 offset:53248
	ds_read_b128 v[202:205], v168 offset:54272
	ds_read_b128 v[206:209], v168 offset:55296
	ds_read_b128 v[210:213], v168 offset:56320
	global_load_lds_dwordx4 v[232:233], off
	s_add_i32 m0, s23, 0x2000
	s_add_u32 s24, s50, 0x80080
	v_lshl_add_u64 v[232:233], v[234:235], 0, s[62:63]
	s_addc_u32 s25, s51, 0
	s_add_i32 s23, s26, s16
	global_load_lds_dwordx4 v[232:233], off
	v_lshl_add_u64 v[232:233], s[24:25], 0, v[132:133]
	s_mov_b32 m0, s23
	s_nop 0
	global_load_lds_dwordx4 v[232:233], off
	v_lshl_add_u64 v[232:233], s[24:25], 0, v[136:137]
	s_add_i32 m0, s23, 0x2000
	s_nop 0
	global_load_lds_dwordx4 v[232:233], off
	v_lshl_add_u64 v[232:233], v[236:237], 0, s[62:63]
	s_mov_b32 m0, s76
	s_nop 0
	global_load_lds_dwordx4 v[232:233], off
	v_lshl_add_u64 v[232:233], v[238:239], 0, s[62:63]
	s_mov_b32 m0, s77
	s_nop 0
	global_load_lds_dwordx4 v[232:233], off
	s_waitcnt vmcnt(8)
	s_waitcnt lgkmcnt(0)
	s_barrier
	s_setprio 1
	s_waitcnt lgkmcnt(0)
	v_mfma_f32_16x16x32_bf16 v[62:65], v[144:147], v[182:185], v[62:65]
	v_mfma_f32_16x16x32_bf16 v[62:65], v[148:151], v[186:189], v[62:65]
	v_mfma_f32_16x16x32_bf16 v[54:57], v[148:151], v[194:197], v[54:57]
	v_mfma_f32_16x16x32_bf16 v[54:57], v[144:147], v[190:193], v[54:57]
	v_mfma_f32_16x16x32_bf16 v[38:41], v[144:147], v[198:201], v[38:41]
	v_mfma_f32_16x16x32_bf16 v[38:41], v[148:151], v[202:205], v[38:41]
	v_mfma_f32_16x16x32_bf16 v[22:25], v[148:151], v[210:213], v[22:25]
	v_mfma_f32_16x16x32_bf16 v[22:25], v[144:147], v[206:209], v[22:25]
	v_mfma_f32_16x16x32_bf16 v[14:17], v[152:155], v[206:209], v[14:17]
	v_mfma_f32_16x16x32_bf16 v[14:17], v[156:159], v[210:213], v[14:17]
	v_mfma_f32_16x16x32_bf16 v[30:33], v[156:159], v[202:205], v[30:33]
	v_mfma_f32_16x16x32_bf16 v[30:33], v[152:155], v[198:201], v[30:33]
	v_mfma_f32_16x16x32_bf16 v[46:49], v[152:155], v[190:193], v[46:49]
	v_mfma_f32_16x16x32_bf16 v[46:49], v[156:159], v[194:197], v[46:49]
	v_mfma_f32_16x16x32_bf16 v[58:61], v[156:159], v[186:189], v[58:61]
	v_mfma_f32_16x16x32_bf16 v[58:61], v[152:155], v[182:185], v[58:61]
	s_setprio 0
	s_setprio 1
	v_mfma_f32_16x16x32_bf16 v[50:53], v[160:163], v[182:185], v[50:53]
	v_mfma_f32_16x16x32_bf16 v[50:53], v[170:173], v[186:189], v[50:53]
	v_mfma_f32_16x16x32_bf16 v[34:37], v[170:173], v[194:197], v[34:37]
	v_mfma_f32_16x16x32_bf16 v[34:37], v[160:163], v[190:193], v[34:37]
	v_mfma_f32_16x16x32_bf16 v[18:21], v[160:163], v[198:201], v[18:21]
	v_mfma_f32_16x16x32_bf16 v[18:21], v[170:173], v[202:205], v[18:21]
	v_mfma_f32_16x16x32_bf16 v[6:9], v[170:173], v[210:213], v[6:9]
	v_mfma_f32_16x16x32_bf16 v[6:9], v[160:163], v[206:209], v[6:9]
	v_mfma_f32_16x16x32_bf16 v[2:5], v[174:177], v[206:209], v[2:5]
	v_mfma_f32_16x16x32_bf16 v[2:5], v[178:181], v[210:213], v[2:5]
	v_mfma_f32_16x16x32_bf16 v[10:13], v[178:181], v[202:205], v[10:13]
	v_mfma_f32_16x16x32_bf16 v[10:13], v[174:177], v[198:201], v[10:13]
	v_mfma_f32_16x16x32_bf16 v[26:29], v[174:177], v[190:193], v[26:29]
	v_mfma_f32_16x16x32_bf16 v[26:29], v[178:181], v[194:197], v[26:29]
	v_mfma_f32_16x16x32_bf16 v[42:45], v[178:181], v[186:189], v[42:45]
	v_mfma_f32_16x16x32_bf16 v[42:45], v[174:177], v[182:185], v[42:45]
	s_setprio 0
	s_barrier
	s_add_i32 s22, s22, 2
	s_add_u32 s48, s48, 0x100
	s_addc_u32 s49, s49, 0
	s_add_u32 s20, s20, 0x100
	s_addc_u32 s21, s21, 0
	s_cmp_gt_u32 s22, 29
	s_cbranch_scc0 .LBB0_132
	s_and_b64 vcc, exec, s[10:11]
	s_cbranch_vccz .LBB0_135
	s_barrier

.LBB0_238:
	s_add_u32 s10, s12, 0x100
	s_addc_u32 s11, s13, 0
	s_add_i32 s23, 0, 0x10000
	s_cmpk_eq_i32 s22, 0x52
	s_cselect_b32 vcc_hi, s47, s11
	s_cselect_b32 vcc_lo, s46, s10
	s_cselect_b32 s51, s49, s21
	s_cselect_b32 s50, s48, s20
	s_add_i32 s24, 0, 0x14000
	v_add_u32_e32 v142, s23, v194
	v_add_u32_e32 v158, s24, v194
	ds_read_b128 v[122:125], v142
	ds_read_b128 v[126:129], v142 offset:1024
	ds_read_b128 v[138:141], v142 offset:2048
	ds_read_b128 v[142:145], v142 offset:3072
	ds_read_b128 v[146:149], v158
	ds_read_b128 v[150:153], v158 offset:1024
	ds_read_b128 v[154:157], v158 offset:2048
	ds_read_b128 v[158:161], v158 offset:3072
	v_lshl_add_u64 v[212:213], s[12:13], 0, v[170:171]
	s_add_i32 m0, s57, 0xc000
	ds_read_b128 v[174:177], v198
	ds_read_b128 v[178:181], v198 offset:1024
	ds_read_b128 v[182:185], v198 offset:2048
	ds_read_b128 v[186:189], v198 offset:3072
	ds_read_b128 v[190:193], v198 offset:4096
	ds_read_b128 v[200:203], v198 offset:5120
	ds_read_b128 v[204:207], v198 offset:6144
	ds_read_b128 v[208:211], v198 offset:7168
	global_load_lds_dwordx4 v[212:213], off
	v_lshl_add_u64 v[212:213], s[12:13], 0, v[172:173]
	s_add_i32 m0, s57, 0xe000
	s_nop 0
	global_load_lds_dwordx4 v[212:213], off
	s_waitcnt vmcnt(8)
	s_waitcnt lgkmcnt(0)
	s_barrier
	s_setprio 1
	s_waitcnt lgkmcnt(0)
	v_mfma_f32_16x16x32_bf16 v[134:137], v[122:125], v[174:177], v[134:137]
	v_mfma_f32_16x16x32_bf16 v[134:137], v[126:129], v[178:181], v[134:137]
	v_mfma_f32_16x16x32_bf16 v[110:113], v[126:129], v[186:189], v[110:113]
	v_mfma_f32_16x16x32_bf16 v[110:113], v[122:125], v[182:185], v[110:113]
	v_mfma_f32_16x16x32_bf16 v[94:97], v[122:125], v[190:193], v[94:97]
	v_mfma_f32_16x16x32_bf16 v[94:97], v[126:129], v[200:203], v[94:97]
	v_mfma_f32_16x16x32_bf16 v[78:81], v[126:129], v[208:211], v[78:81]
	v_mfma_f32_16x16x32_bf16 v[78:81], v[122:125], v[204:207], v[78:81]
	v_mfma_f32_16x16x32_bf16 v[74:77], v[138:141], v[204:207], v[74:77]
	v_mfma_f32_16x16x32_bf16 v[74:77], v[142:145], v[208:211], v[74:77]
	v_mfma_f32_16x16x32_bf16 v[90:93], v[142:145], v[200:203], v[90:93]
	v_mfma_f32_16x16x32_bf16 v[90:93], v[138:141], v[190:193], v[90:93]
	v_mfma_f32_16x16x32_bf16 v[106:109], v[138:141], v[182:185], v[106:109]
	v_mfma_f32_16x16x32_bf16 v[106:109], v[142:145], v[186:189], v[106:109]
	v_mfma_f32_16x16x32_bf16 v[130:133], v[142:145], v[178:181], v[130:133]
	v_mfma_f32_16x16x32_bf16 v[130:133], v[138:141], v[174:177], v[130:133]
	s_setprio 0
	s_setprio 1
	v_mfma_f32_16x16x32_bf16 v[118:121], v[146:149], v[174:177], v[118:121]
	v_mfma_f32_16x16x32_bf16 v[118:121], v[150:153], v[178:181], v[118:121]
	v_mfma_f32_16x16x32_bf16 v[102:105], v[150:153], v[186:189], v[102:105]
	v_mfma_f32_16x16x32_bf16 v[102:105], v[146:149], v[182:185], v[102:105]
	v_mfma_f32_16x16x32_bf16 v[86:89], v[146:149], v[190:193], v[86:89]
	v_mfma_f32_16x16x32_bf16 v[86:89], v[150:153], v[200:203], v[86:89]
	v_mfma_f32_16x16x32_bf16 v[70:73], v[150:153], v[208:211], v[70:73]
	v_mfma_f32_16x16x32_bf16 v[70:73], v[146:149], v[204:207], v[70:73]
	v_mfma_f32_16x16x32_bf16 v[66:69], v[154:157], v[204:207], v[66:69]
	v_mfma_f32_16x16x32_bf16 v[66:69], v[158:161], v[208:211], v[66:69]
	v_mfma_f32_16x16x32_bf16 v[82:85], v[158:161], v[200:203], v[82:85]
	v_mfma_f32_16x16x32_bf16 v[82:85], v[154:157], v[190:193], v[82:85]
	v_mfma_f32_16x16x32_bf16 v[98:101], v[154:157], v[182:185], v[98:101]
	v_mfma_f32_16x16x32_bf16 v[98:101], v[158:161], v[186:189], v[98:101]
	v_mfma_f32_16x16x32_bf16 v[114:117], v[158:161], v[178:181], v[114:117]
	v_mfma_f32_16x16x32_bf16 v[114:117], v[154:157], v[174:177], v[114:117]
	s_setprio 0
	s_barrier
	s_add_i32 s12, s23, s42
	v_lshl_add_u64 v[212:213], s[50:51], 0, v[164:165]
	s_mov_b32 m0, s12
	ds_read_b128 v[174:177], v198 offset:16384
	ds_read_b128 v[178:181], v198 offset:17408
	ds_read_b128 v[182:185], v198 offset:18432
	ds_read_b128 v[186:189], v198 offset:19456
	ds_read_b128 v[190:193], v198 offset:20480
	ds_read_b128 v[200:203], v198 offset:21504
	ds_read_b128 v[204:207], v198 offset:22528
	ds_read_b128 v[208:211], v198 offset:23552
	global_load_lds_dwordx4 v[212:213], off
	s_add_i32 m0, s12, 0x2000
	s_add_u32 s12, s50, 0x158000
	v_lshl_add_u64 v[232:233], s[50:51], 0, v[168:169]
	s_addc_u32 s13, s51, 0
	s_add_i32 s23, s24, s42
	global_load_lds_dwordx4 v[232:233], off
	v_lshl_add_u64 v[234:235], s[12:13], 0, v[164:165]
	s_mov_b32 m0, s23
	v_lshl_add_u64 v[236:237], vcc, 0, v[166:167]
	global_load_lds_dwordx4 v[234:235], off
	v_lshl_add_u64 v[234:235], s[12:13], 0, v[168:169]
	s_add_i32 m0, s23, 0x2000
	s_nop 0
	global_load_lds_dwordx4 v[234:235], off
	v_lshl_add_u64 v[234:235], vcc, 0, v[162:163]
	s_mov_b32 m0, s57
	s_nop 0
	global_load_lds_dwordx4 v[234:235], off
	s_mov_b32 m0, s58
	s_nop 0
	global_load_lds_dwordx4 v[236:237], off
	s_waitcnt vmcnt(8)
	s_waitcnt lgkmcnt(0)
	s_barrier
	s_setprio 1
	s_waitcnt lgkmcnt(0)
	v_mfma_f32_16x16x32_bf16 v[62:65], v[122:125], v[174:177], v[62:65]
	v_mfma_f32_16x16x32_bf16 v[62:65], v[126:129], v[178:181], v[62:65]
	v_mfma_f32_16x16x32_bf16 v[46:49], v[126:129], v[186:189], v[46:49]
	v_mfma_f32_16x16x32_bf16 v[46:49], v[122:125], v[182:185], v[46:49]
	v_mfma_f32_16x16x32_bf16 v[30:33], v[122:125], v[190:193], v[30:33]
	v_mfma_f32_16x16x32_bf16 v[30:33], v[126:129], v[200:203], v[30:33]
	v_mfma_f32_16x16x32_bf16 v[14:17], v[126:129], v[208:211], v[14:17]
	v_mfma_f32_16x16x32_bf16 v[14:17], v[122:125], v[204:207], v[14:17]
	v_mfma_f32_16x16x32_bf16 v[10:13], v[138:141], v[204:207], v[10:13]
	v_mfma_f32_16x16x32_bf16 v[10:13], v[142:145], v[208:211], v[10:13]
	v_mfma_f32_16x16x32_bf16 v[26:29], v[142:145], v[200:203], v[26:29]
	v_mfma_f32_16x16x32_bf16 v[26:29], v[138:141], v[190:193], v[26:29]
	v_mfma_f32_16x16x32_bf16 v[42:45], v[138:141], v[182:185], v[42:45]
	v_mfma_f32_16x16x32_bf16 v[42:45], v[142:145], v[186:189], v[42:45]
	v_mfma_f32_16x16x32_bf16 v[58:61], v[142:145], v[178:181], v[58:61]
	v_mfma_f32_16x16x32_bf16 v[58:61], v[138:141], v[174:177], v[58:61]
	s_setprio 0
	s_setprio 1
	v_mfma_f32_16x16x32_bf16 v[54:57], v[146:149], v[174:177], v[54:57]
	v_mfma_f32_16x16x32_bf16 v[54:57], v[150:153], v[178:181], v[54:57]
	v_mfma_f32_16x16x32_bf16 v[38:41], v[150:153], v[186:189], v[38:41]
	v_mfma_f32_16x16x32_bf16 v[38:41], v[146:149], v[182:185], v[38:41]
	v_mfma_f32_16x16x32_bf16 v[22:25], v[146:149], v[190:193], v[22:25]
	v_mfma_f32_16x16x32_bf16 v[22:25], v[150:153], v[200:203], v[22:25]
	v_mfma_f32_16x16x32_bf16 v[6:9], v[150:153], v[208:211], v[6:9]
	v_mfma_f32_16x16x32_bf16 v[6:9], v[146:149], v[204:207], v[6:9]
	v_mfma_f32_16x16x32_bf16 v[2:5], v[154:157], v[204:207], v[2:5]
	v_mfma_f32_16x16x32_bf16 v[2:5], v[158:161], v[208:211], v[2:5]
	v_mfma_f32_16x16x32_bf16 v[18:21], v[158:161], v[200:203], v[18:21]
	v_mfma_f32_16x16x32_bf16 v[18:21], v[154:157], v[190:193], v[18:21]
	v_mfma_f32_16x16x32_bf16 v[34:37], v[154:157], v[182:185], v[34:37]
	v_mfma_f32_16x16x32_bf16 v[34:37], v[158:161], v[186:189], v[34:37]
	v_mfma_f32_16x16x32_bf16 v[50:53], v[158:161], v[178:181], v[50:53]
	v_mfma_f32_16x16x32_bf16 v[50:53], v[154:157], v[174:177], v[50:53]
	s_setprio 0
	s_barrier
	s_add_i32 s23, 0, 0x18000
	s_add_i32 s24, 0, 0x1c000
	v_add_u32_e32 v142, s23, v194
	v_add_u32_e32 v158, s24, v194
	ds_read_b128 v[122:125], v142
	ds_read_b128 v[126:129], v142 offset:1024
	ds_read_b128 v[138:141], v142 offset:2048
	ds_read_b128 v[142:145], v142 offset:3072
	ds_read_b128 v[146:149], v158
	ds_read_b128 v[150:153], v158 offset:1024
	ds_read_b128 v[154:157], v158 offset:2048
	ds_read_b128 v[158:161], v158 offset:3072
	s_add_u32 s12, vcc_lo, 0x158000
	s_addc_u32 s13, vcc_hi, 0
	s_mov_b32 m0, s67
	v_lshl_add_u64 v[238:239], s[12:13], 0, v[162:163]
	ds_read_b128 v[174:177], v198 offset:32768
	ds_read_b128 v[178:181], v198 offset:33792
	ds_read_b128 v[182:185], v198 offset:34816
	ds_read_b128 v[186:189], v198 offset:35840
	ds_read_b128 v[190:193], v198 offset:36864
	ds_read_b128 v[200:203], v198 offset:37888
	ds_read_b128 v[204:207], v198 offset:38912
	ds_read_b128 v[208:211], v198 offset:39936
	global_load_lds_dwordx4 v[238:239], off
	v_lshl_add_u64 v[238:239], s[12:13], 0, v[166:167]
	s_mov_b32 m0, s76
	s_nop 0
	global_load_lds_dwordx4 v[238:239], off
	s_waitcnt vmcnt(8)
	s_waitcnt lgkmcnt(0)
	s_barrier
	s_setprio 1
	s_waitcnt lgkmcnt(0)
	v_mfma_f32_16x16x32_bf16 v[134:137], v[122:125], v[174:177], v[134:137]
	v_mfma_f32_16x16x32_bf16 v[134:137], v[126:129], v[178:181], v[134:137]
	v_mfma_f32_16x16x32_bf16 v[110:113], v[126:129], v[186:189], v[110:113]
	v_mfma_f32_16x16x32_bf16 v[110:113], v[122:125], v[182:185], v[110:113]
	v_mfma_f32_16x16x32_bf16 v[94:97], v[122:125], v[190:193], v[94:97]
	v_mfma_f32_16x16x32_bf16 v[94:97], v[126:129], v[200:203], v[94:97]
	v_mfma_f32_16x16x32_bf16 v[78:81], v[126:129], v[208:211], v[78:81]
	v_mfma_f32_16x16x32_bf16 v[78:81], v[122:125], v[204:207], v[78:81]
	v_mfma_f32_16x16x32_bf16 v[74:77], v[138:141], v[204:207], v[74:77]
	v_mfma_f32_16x16x32_bf16 v[74:77], v[142:145], v[208:211], v[74:77]
	v_mfma_f32_16x16x32_bf16 v[90:93], v[142:145], v[200:203], v[90:93]
	v_mfma_f32_16x16x32_bf16 v[90:93], v[138:141], v[190:193], v[90:93]
	v_mfma_f32_16x16x32_bf16 v[106:109], v[138:141], v[182:185], v[106:109]
	v_mfma_f32_16x16x32_bf16 v[106:109], v[142:145], v[186:189], v[106:109]
	v_mfma_f32_16x16x32_bf16 v[130:133], v[142:145], v[178:181], v[130:133]
	v_mfma_f32_16x16x32_bf16 v[130:133], v[138:141], v[174:177], v[130:133]
	s_setprio 0
	s_setprio 1
	v_mfma_f32_16x16x32_bf16 v[118:121], v[146:149], v[174:177], v[118:121]
	v_mfma_f32_16x16x32_bf16 v[118:121], v[150:153], v[178:181], v[118:121]
	v_mfma_f32_16x16x32_bf16 v[102:105], v[150:153], v[186:189], v[102:105]
	v_mfma_f32_16x16x32_bf16 v[102:105], v[146:149], v[182:185], v[102:105]
	v_mfma_f32_16x16x32_bf16 v[86:89], v[146:149], v[190:193], v[86:89]
	v_mfma_f32_16x16x32_bf16 v[86:89], v[150:153], v[200:203], v[86:89]
	v_mfma_f32_16x16x32_bf16 v[70:73], v[150:153], v[208:211], v[70:73]
	v_mfma_f32_16x16x32_bf16 v[70:73], v[146:149], v[204:207], v[70:73]
	v_mfma_f32_16x16x32_bf16 v[66:69], v[154:157], v[204:207], v[66:69]
	v_mfma_f32_16x16x32_bf16 v[66:69], v[158:161], v[208:211], v[66:69]
	v_mfma_f32_16x16x32_bf16 v[82:85], v[158:161], v[200:203], v[82:85]
	v_mfma_f32_16x16x32_bf16 v[82:85], v[154:157], v[190:193], v[82:85]
	v_mfma_f32_16x16x32_bf16 v[98:101], v[154:157], v[182:185], v[98:101]
	v_mfma_f32_16x16x32_bf16 v[98:101], v[158:161], v[186:189], v[98:101]
	v_mfma_f32_16x16x32_bf16 v[114:117], v[158:161], v[178:181], v[114:117]
	v_mfma_f32_16x16x32_bf16 v[114:117], v[154:157], v[174:177], v[114:117]
	s_setprio 0
	s_barrier
	s_add_i32 s12, s23, s42
	v_lshl_add_u64 v[212:213], v[212:213], 0, s[62:63]
	s_mov_b32 m0, s12
	ds_read_b128 v[174:177], v198 offset:49152
	ds_read_b128 v[178:181], v198 offset:50176
	ds_read_b128 v[182:185], v198 offset:51200
	ds_read_b128 v[186:189], v198 offset:52224
	ds_read_b128 v[190:193], v198 offset:53248
	ds_read_b128 v[200:203], v198 offset:54272
	ds_read_b128 v[204:207], v198 offset:55296
	ds_read_b128 v[208:211], v198 offset:56320
	global_load_lds_dwordx4 v[212:213], off
	s_add_i32 m0, s12, 0x2000
	s_add_u32 s12, s50, 0x158080
	v_lshl_add_u64 v[212:213], v[232:233], 0, s[62:63]
	s_addc_u32 s13, s51, 0
	s_add_i32 s23, s24, s42
	global_load_lds_dwordx4 v[212:213], off
	v_lshl_add_u64 v[212:213], s[12:13], 0, v[164:165]
	s_mov_b32 m0, s23
	s_nop 0
	global_load_lds_dwordx4 v[212:213], off
	v_lshl_add_u64 v[212:213], s[12:13], 0, v[168:169]
	s_add_i32 m0, s23, 0x2000
	s_nop 0
	global_load_lds_dwordx4 v[212:213], off
	v_lshl_add_u64 v[212:213], v[234:235], 0, s[62:63]
	s_mov_b32 m0, s1
	s_nop 0
	global_load_lds_dwordx4 v[212:213], off
	v_lshl_add_u64 v[212:213], v[236:237], 0, s[62:63]
	s_mov_b32 m0, s52
	s_nop 0
	global_load_lds_dwordx4 v[212:213], off
	s_waitcnt vmcnt(8)
	s_waitcnt lgkmcnt(0)
	s_barrier
	s_setprio 1
	s_waitcnt lgkmcnt(0)
	v_mfma_f32_16x16x32_bf16 v[62:65], v[122:125], v[174:177], v[62:65]
	v_mfma_f32_16x16x32_bf16 v[62:65], v[126:129], v[178:181], v[62:65]
	v_mfma_f32_16x16x32_bf16 v[46:49], v[126:129], v[186:189], v[46:49]
	v_mfma_f32_16x16x32_bf16 v[46:49], v[122:125], v[182:185], v[46:49]
	v_mfma_f32_16x16x32_bf16 v[30:33], v[122:125], v[190:193], v[30:33]
	v_mfma_f32_16x16x32_bf16 v[30:33], v[126:129], v[200:203], v[30:33]
	v_mfma_f32_16x16x32_bf16 v[14:17], v[126:129], v[208:211], v[14:17]
	v_mfma_f32_16x16x32_bf16 v[14:17], v[122:125], v[204:207], v[14:17]
	v_mfma_f32_16x16x32_bf16 v[10:13], v[138:141], v[204:207], v[10:13]
	v_mfma_f32_16x16x32_bf16 v[10:13], v[142:145], v[208:211], v[10:13]
	v_mfma_f32_16x16x32_bf16 v[26:29], v[142:145], v[200:203], v[26:29]
	v_mfma_f32_16x16x32_bf16 v[26:29], v[138:141], v[190:193], v[26:29]
	v_mfma_f32_16x16x32_bf16 v[42:45], v[138:141], v[182:185], v[42:45]
	v_mfma_f32_16x16x32_bf16 v[42:45], v[142:145], v[186:189], v[42:45]
	v_mfma_f32_16x16x32_bf16 v[58:61], v[142:145], v[178:181], v[58:61]
	v_mfma_f32_16x16x32_bf16 v[58:61], v[138:141], v[174:177], v[58:61]
	s_setprio 0
	s_setprio 1
	v_mfma_f32_16x16x32_bf16 v[54:57], v[146:149], v[174:177], v[54:57]
	v_mfma_f32_16x16x32_bf16 v[54:57], v[150:153], v[178:181], v[54:57]
	v_mfma_f32_16x16x32_bf16 v[38:41], v[150:153], v[186:189], v[38:41]
	v_mfma_f32_16x16x32_bf16 v[38:41], v[146:149], v[182:185], v[38:41]
	v_mfma_f32_16x16x32_bf16 v[22:25], v[146:149], v[190:193], v[22:25]
	v_mfma_f32_16x16x32_bf16 v[22:25], v[150:153], v[200:203], v[22:25]
	v_mfma_f32_16x16x32_bf16 v[6:9], v[150:153], v[208:211], v[6:9]
	v_mfma_f32_16x16x32_bf16 v[6:9], v[146:149], v[204:207], v[6:9]
	v_mfma_f32_16x16x32_bf16 v[2:5], v[154:157], v[204:207], v[2:5]
	v_mfma_f32_16x16x32_bf16 v[2:5], v[158:161], v[208:211], v[2:5]
	v_mfma_f32_16x16x32_bf16 v[18:21], v[158:161], v[200:203], v[18:21]
	v_mfma_f32_16x16x32_bf16 v[18:21], v[154:157], v[190:193], v[18:21]
	v_mfma_f32_16x16x32_bf16 v[34:37], v[154:157], v[182:185], v[34:37]
	v_mfma_f32_16x16x32_bf16 v[34:37], v[158:161], v[186:189], v[34:37]
	v_mfma_f32_16x16x32_bf16 v[50:53], v[158:161], v[178:181], v[50:53]
	v_mfma_f32_16x16x32_bf16 v[50:53], v[154:157], v[174:177], v[50:53]
	s_setprio 0
	s_barrier
	s_add_i32 s22, s22, 2
	s_add_u32 s20, s20, 0x100
	s_addc_u32 s21, s21, 0
	s_cmpk_gt_u32 s22, 0x53
	s_mov_b64 s[12:13], s[10:11]
	s_cbranch_scc0 .LBB0_238
	s_and_b64 vcc, exec, s[2:3]
	s_cbranch_vccz .LBB0_241
	s_barrier

.LBB0_340:
	s_add_u32 s22, s46, 0xfff80080
	s_addc_u32 s23, s47, -1
	s_add_i32 s24, 0, 0x10000
	s_cmp_eq_u32 s21, 28
	s_cselect_b32 s51, s1, s23
	s_cselect_b32 s50, s13, s22
	v_add_u32_e32 v148, s24, v152
	s_cselect_b32 s49, s11, s20
	s_cselect_b32 s48, s18, s19
	s_add_i32 s25, 0, 0x14000
	ds_read_b128 v[144:147], v148
	ds_read_b128 v[156:159], v148 offset:1024
	ds_read_b128 v[160:163], v148 offset:2048
	ds_read_b128 v[164:167], v148 offset:3072
	v_add_u32_e32 v148, s25, v152
	ds_read_b128 v[168:171], v148
	ds_read_b128 v[172:175], v148 offset:1024
	ds_read_b128 v[176:179], v148 offset:2048
	ds_read_b128 v[180:183], v148 offset:3072
	v_lshl_add_u64 v[148:149], s[46:47], 0, v[140:141]
	s_add_i32 m0, s3, 0xc000
	ds_read_b128 v[184:187], v154
	ds_read_b128 v[188:191], v154 offset:1024
	ds_read_b128 v[192:195], v154 offset:2048
	ds_read_b128 v[196:199], v154 offset:3072
	ds_read_b128 v[200:203], v154 offset:4096
	ds_read_b128 v[204:207], v154 offset:5120
	ds_read_b128 v[208:211], v154 offset:6144
	ds_read_b128 v[232:235], v154 offset:7168
	global_load_lds_dwordx4 v[148:149], off
	v_lshl_add_u64 v[148:149], s[46:47], 0, v[142:143]
	s_add_i32 m0, s3, 0xe000
	s_nop 0
	global_load_lds_dwordx4 v[148:149], off
	s_waitcnt vmcnt(8)
	s_waitcnt lgkmcnt(0)
	s_barrier
	s_setprio 1
	s_waitcnt lgkmcnt(0)
	v_mfma_f32_16x16x32_bf16 v[126:129], v[144:147], v[184:187], v[126:129]
	v_mfma_f32_16x16x32_bf16 v[126:129], v[156:159], v[188:191], v[126:129]
	v_mfma_f32_16x16x32_bf16 v[110:113], v[156:159], v[196:199], v[110:113]
	v_mfma_f32_16x16x32_bf16 v[110:113], v[144:147], v[192:195], v[110:113]
	v_mfma_f32_16x16x32_bf16 v[94:97], v[144:147], v[200:203], v[94:97]
	v_mfma_f32_16x16x32_bf16 v[94:97], v[156:159], v[204:207], v[94:97]
	v_mfma_f32_16x16x32_bf16 v[78:81], v[156:159], v[232:235], v[78:81]
	v_mfma_f32_16x16x32_bf16 v[78:81], v[144:147], v[208:211], v[78:81]
	v_mfma_f32_16x16x32_bf16 v[74:77], v[160:163], v[208:211], v[74:77]
	v_mfma_f32_16x16x32_bf16 v[74:77], v[164:167], v[232:235], v[74:77]
	v_mfma_f32_16x16x32_bf16 v[90:93], v[164:167], v[204:207], v[90:93]
	v_mfma_f32_16x16x32_bf16 v[90:93], v[160:163], v[200:203], v[90:93]
	v_mfma_f32_16x16x32_bf16 v[106:109], v[160:163], v[192:195], v[106:109]
	v_mfma_f32_16x16x32_bf16 v[106:109], v[164:167], v[196:199], v[106:109]
	v_mfma_f32_16x16x32_bf16 v[122:125], v[164:167], v[188:191], v[122:125]
	v_mfma_f32_16x16x32_bf16 v[122:125], v[160:163], v[184:187], v[122:125]
	s_setprio 0
	s_setprio 1
	v_mfma_f32_16x16x32_bf16 v[118:121], v[168:171], v[184:187], v[118:121]
	v_mfma_f32_16x16x32_bf16 v[118:121], v[172:175], v[188:191], v[118:121]
	v_mfma_f32_16x16x32_bf16 v[102:105], v[172:175], v[196:199], v[102:105]
	v_mfma_f32_16x16x32_bf16 v[102:105], v[168:171], v[192:195], v[102:105]
	v_mfma_f32_16x16x32_bf16 v[86:89], v[168:171], v[200:203], v[86:89]
	v_mfma_f32_16x16x32_bf16 v[86:89], v[172:175], v[204:207], v[86:89]
	v_mfma_f32_16x16x32_bf16 v[70:73], v[172:175], v[232:235], v[70:73]
	v_mfma_f32_16x16x32_bf16 v[70:73], v[168:171], v[208:211], v[70:73]
	v_mfma_f32_16x16x32_bf16 v[66:69], v[176:179], v[208:211], v[66:69]
	v_mfma_f32_16x16x32_bf16 v[66:69], v[180:183], v[232:235], v[66:69]
	v_mfma_f32_16x16x32_bf16 v[82:85], v[180:183], v[204:207], v[82:85]
	v_mfma_f32_16x16x32_bf16 v[82:85], v[176:179], v[200:203], v[82:85]
	v_mfma_f32_16x16x32_bf16 v[98:101], v[176:179], v[192:195], v[98:101]
	v_mfma_f32_16x16x32_bf16 v[98:101], v[180:183], v[196:199], v[98:101]
	v_mfma_f32_16x16x32_bf16 v[114:117], v[180:183], v[188:191], v[114:117]
	v_mfma_f32_16x16x32_bf16 v[114:117], v[176:179], v[184:187], v[114:117]
	s_setprio 0
	s_barrier
	s_add_i32 s22, s24, s16
	v_lshl_add_u64 v[148:149], s[48:49], 0, v[134:135]
	s_mov_b32 m0, s22
	ds_read_b128 v[184:187], v154 offset:16384
	ds_read_b128 v[188:191], v154 offset:17408
	ds_read_b128 v[192:195], v154 offset:18432
	ds_read_b128 v[196:199], v154 offset:19456
	ds_read_b128 v[200:203], v154 offset:20480
	ds_read_b128 v[204:207], v154 offset:21504
	ds_read_b128 v[208:211], v154 offset:22528
	ds_read_b128 v[232:235], v154 offset:23552
	global_load_lds_dwordx4 v[148:149], off
	s_add_i32 m0, s22, 0x2000
	s_add_u32 s22, s48, 0x80000
	v_lshl_add_u64 v[212:213], s[48:49], 0, v[130:131]
	s_addc_u32 s23, s49, 0
	s_add_i32 s24, s25, s16
	global_load_lds_dwordx4 v[212:213], off
	v_lshl_add_u64 v[236:237], s[22:23], 0, v[134:135]
	s_mov_b32 m0, s24
	v_lshl_add_u64 v[238:239], s[50:51], 0, v[132:133]
	global_load_lds_dwordx4 v[236:237], off
	v_lshl_add_u64 v[236:237], s[22:23], 0, v[130:131]
	s_add_i32 m0, s24, 0x2000
	s_nop 0
	global_load_lds_dwordx4 v[236:237], off
	v_lshl_add_u64 v[236:237], s[50:51], 0, v[136:137]
	s_mov_b32 m0, s3
	s_nop 0
	global_load_lds_dwordx4 v[236:237], off
	s_mov_b32 m0, s55
	s_nop 0
	global_load_lds_dwordx4 v[238:239], off
	s_waitcnt vmcnt(8)
	s_waitcnt lgkmcnt(0)
	s_barrier
	s_setprio 1
	s_waitcnt lgkmcnt(0)
	v_mfma_f32_16x16x32_bf16 v[62:65], v[144:147], v[184:187], v[62:65]
	v_mfma_f32_16x16x32_bf16 v[62:65], v[156:159], v[188:191], v[62:65]
	v_mfma_f32_16x16x32_bf16 v[46:49], v[156:159], v[196:199], v[46:49]
	v_mfma_f32_16x16x32_bf16 v[46:49], v[144:147], v[192:195], v[46:49]
	v_mfma_f32_16x16x32_bf16 v[30:33], v[144:147], v[200:203], v[30:33]
	v_mfma_f32_16x16x32_bf16 v[30:33], v[156:159], v[204:207], v[30:33]
	v_mfma_f32_16x16x32_bf16 v[14:17], v[156:159], v[232:235], v[14:17]
	v_mfma_f32_16x16x32_bf16 v[14:17], v[144:147], v[208:211], v[14:17]
	v_mfma_f32_16x16x32_bf16 v[10:13], v[160:163], v[208:211], v[10:13]
	v_mfma_f32_16x16x32_bf16 v[10:13], v[164:167], v[232:235], v[10:13]
	v_mfma_f32_16x16x32_bf16 v[26:29], v[164:167], v[204:207], v[26:29]
	v_mfma_f32_16x16x32_bf16 v[26:29], v[160:163], v[200:203], v[26:29]
	v_mfma_f32_16x16x32_bf16 v[42:45], v[160:163], v[192:195], v[42:45]
	v_mfma_f32_16x16x32_bf16 v[42:45], v[164:167], v[196:199], v[42:45]
	v_mfma_f32_16x16x32_bf16 v[58:61], v[164:167], v[188:191], v[58:61]
	v_mfma_f32_16x16x32_bf16 v[58:61], v[160:163], v[184:187], v[58:61]
	s_setprio 0
	s_setprio 1
	v_mfma_f32_16x16x32_bf16 v[54:57], v[168:171], v[184:187], v[54:57]
	v_mfma_f32_16x16x32_bf16 v[54:57], v[172:175], v[188:191], v[54:57]
	v_mfma_f32_16x16x32_bf16 v[38:41], v[172:175], v[196:199], v[38:41]
	v_mfma_f32_16x16x32_bf16 v[38:41], v[168:171], v[192:195], v[38:41]
	v_mfma_f32_16x16x32_bf16 v[22:25], v[168:171], v[200:203], v[22:25]
	v_mfma_f32_16x16x32_bf16 v[22:25], v[172:175], v[204:207], v[22:25]
	v_mfma_f32_16x16x32_bf16 v[6:9], v[172:175], v[232:235], v[6:9]
	v_mfma_f32_16x16x32_bf16 v[6:9], v[168:171], v[208:211], v[6:9]
	v_mfma_f32_16x16x32_bf16 v[2:5], v[176:179], v[208:211], v[2:5]
	v_mfma_f32_16x16x32_bf16 v[2:5], v[180:183], v[232:235], v[2:5]
	v_mfma_f32_16x16x32_bf16 v[18:21], v[180:183], v[204:207], v[18:21]
	v_mfma_f32_16x16x32_bf16 v[18:21], v[176:179], v[200:203], v[18:21]
	v_mfma_f32_16x16x32_bf16 v[34:37], v[176:179], v[192:195], v[34:37]
	v_mfma_f32_16x16x32_bf16 v[34:37], v[180:183], v[196:199], v[34:37]
	v_mfma_f32_16x16x32_bf16 v[50:53], v[180:183], v[188:191], v[50:53]
	v_mfma_f32_16x16x32_bf16 v[50:53], v[176:179], v[184:187], v[50:53]
	s_setprio 0
	s_barrier
	s_add_i32 s24, 0, 0x18000
	v_add_u32_e32 v155, s24, v152
	s_add_i32 s25, 0, 0x1c000
	ds_read_b128 v[144:147], v155
	ds_read_b128 v[156:159], v155 offset:1024
	ds_read_b128 v[160:163], v155 offset:2048
	ds_read_b128 v[164:167], v155 offset:3072
	v_add_u32_e32 v155, s25, v152
	ds_read_b128 v[168:171], v155
	ds_read_b128 v[172:175], v155 offset:1024
	ds_read_b128 v[176:179], v155 offset:2048
	ds_read_b128 v[180:183], v155 offset:3072
	s_add_u32 s22, s50, 0x80000
	s_addc_u32 s23, s51, 0
	s_mov_b32 m0, s57
	v_lshl_add_u64 v[240:241], s[22:23], 0, v[136:137]
	ds_read_b128 v[184:187], v154 offset:32768
	ds_read_b128 v[188:191], v154 offset:33792
	ds_read_b128 v[192:195], v154 offset:34816
	ds_read_b128 v[196:199], v154 offset:35840
	ds_read_b128 v[200:203], v154 offset:36864
	ds_read_b128 v[204:207], v154 offset:37888
	ds_read_b128 v[208:211], v154 offset:38912
	ds_read_b128 v[232:235], v154 offset:39936
	global_load_lds_dwordx4 v[240:241], off
	v_lshl_add_u64 v[240:241], s[22:23], 0, v[132:133]
	s_mov_b32 m0, s68
	s_nop 0
	global_load_lds_dwordx4 v[240:241], off
	s_waitcnt vmcnt(8)
	s_waitcnt lgkmcnt(0)
	s_barrier
	s_setprio 1
	s_waitcnt lgkmcnt(0)
	v_mfma_f32_16x16x32_bf16 v[126:129], v[144:147], v[184:187], v[126:129]
	v_mfma_f32_16x16x32_bf16 v[126:129], v[156:159], v[188:191], v[126:129]
	v_mfma_f32_16x16x32_bf16 v[110:113], v[156:159], v[196:199], v[110:113]
	v_mfma_f32_16x16x32_bf16 v[110:113], v[144:147], v[192:195], v[110:113]
	v_mfma_f32_16x16x32_bf16 v[94:97], v[144:147], v[200:203], v[94:97]
	v_mfma_f32_16x16x32_bf16 v[94:97], v[156:159], v[204:207], v[94:97]
	v_mfma_f32_16x16x32_bf16 v[78:81], v[156:159], v[232:235], v[78:81]
	v_mfma_f32_16x16x32_bf16 v[78:81], v[144:147], v[208:211], v[78:81]
	v_mfma_f32_16x16x32_bf16 v[74:77], v[160:163], v[208:211], v[74:77]
	v_mfma_f32_16x16x32_bf16 v[74:77], v[164:167], v[232:235], v[74:77]
	v_mfma_f32_16x16x32_bf16 v[90:93], v[164:167], v[204:207], v[90:93]
	v_mfma_f32_16x16x32_bf16 v[90:93], v[160:163], v[200:203], v[90:93]
	v_mfma_f32_16x16x32_bf16 v[106:109], v[160:163], v[192:195], v[106:109]
	v_mfma_f32_16x16x32_bf16 v[106:109], v[164:167], v[196:199], v[106:109]
	v_mfma_f32_16x16x32_bf16 v[122:125], v[164:167], v[188:191], v[122:125]
	v_mfma_f32_16x16x32_bf16 v[122:125], v[160:163], v[184:187], v[122:125]
	s_setprio 0
	s_setprio 1
	v_mfma_f32_16x16x32_bf16 v[118:121], v[168:171], v[184:187], v[118:121]
	v_mfma_f32_16x16x32_bf16 v[118:121], v[172:175], v[188:191], v[118:121]
	v_mfma_f32_16x16x32_bf16 v[102:105], v[172:175], v[196:199], v[102:105]
	v_mfma_f32_16x16x32_bf16 v[102:105], v[168:171], v[192:195], v[102:105]
	v_mfma_f32_16x16x32_bf16 v[86:89], v[168:171], v[200:203], v[86:89]
	v_mfma_f32_16x16x32_bf16 v[86:89], v[172:175], v[204:207], v[86:89]
	v_mfma_f32_16x16x32_bf16 v[70:73], v[172:175], v[232:235], v[70:73]
	v_mfma_f32_16x16x32_bf16 v[70:73], v[168:171], v[208:211], v[70:73]
	v_mfma_f32_16x16x32_bf16 v[66:69], v[176:179], v[208:211], v[66:69]
	v_mfma_f32_16x16x32_bf16 v[66:69], v[180:183], v[232:235], v[66:69]
	v_mfma_f32_16x16x32_bf16 v[82:85], v[180:183], v[204:207], v[82:85]
	v_mfma_f32_16x16x32_bf16 v[82:85], v[176:179], v[200:203], v[82:85]
	v_mfma_f32_16x16x32_bf16 v[98:101], v[176:179], v[192:195], v[98:101]
	v_mfma_f32_16x16x32_bf16 v[98:101], v[180:183], v[196:199], v[98:101]
	v_mfma_f32_16x16x32_bf16 v[114:117], v[180:183], v[188:191], v[114:117]
	v_mfma_f32_16x16x32_bf16 v[114:117], v[176:179], v[184:187], v[114:117]
	s_setprio 0
	s_barrier
	s_add_i32 s22, s24, s16
	v_lshl_add_u64 v[148:149], v[148:149], 0, s[62:63]
	s_mov_b32 m0, s22
	ds_read_b128 v[184:187], v154 offset:49152
	ds_read_b128 v[188:191], v154 offset:50176
	ds_read_b128 v[192:195], v154 offset:51200
	ds_read_b128 v[196:199], v154 offset:52224
	ds_read_b128 v[200:203], v154 offset:53248
	ds_read_b128 v[204:207], v154 offset:54272
	ds_read_b128 v[208:211], v154 offset:55296
	ds_read_b128 v[232:235], v154 offset:56320
	global_load_lds_dwordx4 v[148:149], off
	s_add_i32 m0, s22, 0x2000
	s_add_u32 s22, s48, 0x80080
	v_lshl_add_u64 v[148:149], v[212:213], 0, s[62:63]
	s_addc_u32 s23, s49, 0
	s_add_i32 s24, s25, s16
	global_load_lds_dwordx4 v[148:149], off
	v_lshl_add_u64 v[148:149], s[22:23], 0, v[134:135]
	s_mov_b32 m0, s24
	s_nop 0
	global_load_lds_dwordx4 v[148:149], off
	v_lshl_add_u64 v[148:149], s[22:23], 0, v[130:131]
	s_add_i32 m0, s24, 0x2000
	s_nop 0
	global_load_lds_dwordx4 v[148:149], off
	v_lshl_add_u64 v[148:149], v[236:237], 0, s[62:63]
	s_mov_b32 m0, s69
	s_nop 0
	global_load_lds_dwordx4 v[148:149], off
	v_lshl_add_u64 v[148:149], v[238:239], 0, s[62:63]
	s_mov_b32 m0, s70
	s_nop 0
	global_load_lds_dwordx4 v[148:149], off
	s_waitcnt vmcnt(8)
	s_waitcnt lgkmcnt(0)
	s_barrier
	s_setprio 1
	s_waitcnt lgkmcnt(0)
	v_mfma_f32_16x16x32_bf16 v[62:65], v[144:147], v[184:187], v[62:65]
	v_mfma_f32_16x16x32_bf16 v[62:65], v[156:159], v[188:191], v[62:65]
	v_mfma_f32_16x16x32_bf16 v[46:49], v[156:159], v[196:199], v[46:49]
	v_mfma_f32_16x16x32_bf16 v[46:49], v[144:147], v[192:195], v[46:49]
	v_mfma_f32_16x16x32_bf16 v[30:33], v[144:147], v[200:203], v[30:33]
	v_mfma_f32_16x16x32_bf16 v[30:33], v[156:159], v[204:207], v[30:33]
	v_mfma_f32_16x16x32_bf16 v[14:17], v[156:159], v[232:235], v[14:17]
	v_mfma_f32_16x16x32_bf16 v[14:17], v[144:147], v[208:211], v[14:17]
	v_mfma_f32_16x16x32_bf16 v[10:13], v[160:163], v[208:211], v[10:13]
	v_mfma_f32_16x16x32_bf16 v[10:13], v[164:167], v[232:235], v[10:13]
	v_mfma_f32_16x16x32_bf16 v[26:29], v[164:167], v[204:207], v[26:29]
	v_mfma_f32_16x16x32_bf16 v[26:29], v[160:163], v[200:203], v[26:29]
	v_mfma_f32_16x16x32_bf16 v[42:45], v[160:163], v[192:195], v[42:45]
	v_mfma_f32_16x16x32_bf16 v[42:45], v[164:167], v[196:199], v[42:45]
	v_mfma_f32_16x16x32_bf16 v[58:61], v[164:167], v[188:191], v[58:61]
	v_mfma_f32_16x16x32_bf16 v[58:61], v[160:163], v[184:187], v[58:61]
	s_setprio 0
	s_setprio 1
	v_mfma_f32_16x16x32_bf16 v[54:57], v[168:171], v[184:187], v[54:57]
	v_mfma_f32_16x16x32_bf16 v[54:57], v[172:175], v[188:191], v[54:57]
	v_mfma_f32_16x16x32_bf16 v[38:41], v[172:175], v[196:199], v[38:41]
	v_mfma_f32_16x16x32_bf16 v[38:41], v[168:171], v[192:195], v[38:41]
	v_mfma_f32_16x16x32_bf16 v[22:25], v[168:171], v[200:203], v[22:25]
	v_mfma_f32_16x16x32_bf16 v[22:25], v[172:175], v[204:207], v[22:25]
	v_mfma_f32_16x16x32_bf16 v[6:9], v[172:175], v[232:235], v[6:9]
	v_mfma_f32_16x16x32_bf16 v[6:9], v[168:171], v[208:211], v[6:9]
	v_mfma_f32_16x16x32_bf16 v[2:5], v[176:179], v[208:211], v[2:5]
	v_mfma_f32_16x16x32_bf16 v[2:5], v[180:183], v[232:235], v[2:5]
	v_mfma_f32_16x16x32_bf16 v[18:21], v[180:183], v[204:207], v[18:21]
	v_mfma_f32_16x16x32_bf16 v[18:21], v[176:179], v[200:203], v[18:21]
	v_mfma_f32_16x16x32_bf16 v[34:37], v[176:179], v[192:195], v[34:37]
	v_mfma_f32_16x16x32_bf16 v[34:37], v[180:183], v[196:199], v[34:37]
	v_mfma_f32_16x16x32_bf16 v[50:53], v[180:183], v[188:191], v[50:53]
	v_mfma_f32_16x16x32_bf16 v[50:53], v[176:179], v[184:187], v[50:53]
	s_setprio 0
	s_barrier
	s_add_i32 s21, s21, 2
	s_add_u32 s46, s46, 0x100
	s_addc_u32 s47, s47, 0
	s_add_u32 s19, s19, 0x100
	s_addc_u32 s20, s20, 0
	s_cmp_gt_u32 s21, 29
	s_cbranch_scc0 .LBB0_340
	s_and_b64 vcc, exec, s[8:9]
	s_cbranch_vccz .LBB0_343
	s_barrier
